# conv U staging: chunk halo elements taken from neighbouring lanes (DPP wave_shr/wave_shl); only lane 0 / lane 63 still issue the 2-byte loads
# baseline (speedup 1.0000x reference)
; template <int NQ, int NB, int L>
; __device__ __forceinline__ void conv_unit(LAS unsigned char* lds, const Args& a, int j, int seq0, int c, int tid) {
;     ...
;     const float* cw = a.in[7] + (size_t)j * 3 * 3072; const float* cb = a.in[8] + (size_t)j * 3072;
;     constexpr int NF = (LEN / 8 + 511) / 512;
;     u32x4 fkr[NF];
;     {
;         const u32x4* src = (const u32x4*)(FK + (size_t)c * LEN);
; #pragma unroll
;         for (int it = 0; it < NF; ++it) { const int i = it * 512 + tid; fkr[it] = src[i < LEN / 8 ? i : 0]; }
;     }
;     {
;         const float w0 = cw[2048 + c], w1 = cw[3072 + 2048 + c], w2 = cw[2 * 3072 + 2048 + c], bb = cb[2048 + c];
;         constexpr int NCH = LPD / 8, NIT = (NB * NCH + 511) / 512;
;         u32x4 raws[NIT]; unsigned halos[NIT];
; #pragma unroll
;         for (int it = 0; it < NIT; ++it) {
;             const int idx = it * 512 + tid; const int b = idx / NCH, ch = idx % NCH, p = ch * 8 - PADL;
;             raws[it] = (u32x4){0u, 0u, 0u, 0u}; halos[it] = 0u;
;             if (idx < NB * NCH && p >= 0 && p < L) {
;                 const bf16_t* row = V + seq_off_ch(seq0 + b) + (size_t)c * LS + XPAD + p;
;                 raws[it] = *(const u32x4*)row;
;                 const unsigned xm = p > 0 ? (unsigned)row[-1] : 0u, xp = (p + 8 < L) ? (unsigned)row[8] : 0u;
;                 halos[it] = xm | (xp << 16);
;             }
;         }
.LBB0_1178:
	s_mov_b32 s92, 1
	s_mov_b32 s93, 0
	s_mov_b32 s94, 0
	s_mov_b32 s95, 0x80000000
	v_mov_b32_e32 v190, v215
	s_movk_i32 s4, 0x480
	s_movk_i32 s6, 0x280
	s_movk_i32 s8, 0x80
	s_mov_b64 s[2:3], -1
	s_cmpk_gt_i32 s52, 0x3ff
	v_cmp_gt_i32_e64 s[4:5], s4, v190
	v_add_u32_e32 v191, 0x200, v190
	v_cmp_gt_i32_e64 s[6:7], s6, v190
	v_add_u32_e32 v192, 0x400, v190
	v_cmp_gt_i32_e64 s[8:9], s8, v190
	s_cbranch_scc0 .LBB0_1429
	v_mov_b32_e32 v110, 0
	v_mov_b32_e32 v111, 0
	v_mov_b32_e32 v112, 0
	v_mov_b32_e32 v113, 0
	v_mov_b32_e32 v114, 0
	v_mov_b32_e32 v115, 0
	v_mov_b32_e32 v116, 0
	v_mov_b32_e32 v117, 0
	v_mov_b32_e32 v118, 0
	v_mov_b32_e32 v119, 0
	v_mov_b32_e32 v120, 0
	v_mov_b32_e32 v121, 0
	v_mov_b32_e32 v122, 0
	v_mov_b32_e32 v123, 0
	v_mov_b32_e32 v124, 0
	v_mov_b32_e32 v125, 0
	v_mov_b32_e32 v126, 0
	v_mov_b32_e32 v127, 0
	v_mov_b32_e32 v128, 0
	v_mov_b32_e32 v129, 0
	s_add_i32 s2, s52, 0xfffffc00
	s_lshl_b32 s3, s52, 3
	s_and_b32 s53, s3, 8
	s_lshr_b32 s62, s2, 1
	s_or_b32 s50, s53, 4
	s_mul_i32 s3, s62, 0x4800
	v_readlane_b32 s10, v254, 19
	s_mul_hi_u32 s2, s62, 0x4800
	s_add_u32 s66, s10, s3
	v_readlane_b32 s3, v254, 21
	s_addc_u32 s67, s3, s2
	s_or_b32 s56, s62, 0x800
	s_lshl_b64 s[2:3], s[56:57], 2
	s_mov_b32 s63, s57
	s_add_u32 s10, s87, s2
	v_cndmask_b32_e64 v58, 0, v190, s[4:5]
	v_cndmask_b32_e64 v60, 0, v191, s[6:7]
	s_addc_u32 s11, s88, s3
	s_lshl_b64 s[12:13], s[62:63], 2
	v_ashrrev_i32_e32 v59, 31, v58
	v_ashrrev_i32_e32 v61, 31, v60
	v_cndmask_b32_e64 v62, 0, v192, s[8:9]
	s_add_u32 s12, s87, s12
	v_lshl_add_u64 v[0:1], v[58:59], 4, s[66:67]
	v_lshl_add_u64 v[4:5], v[60:61], 4, s[66:67]
	v_ashrrev_i32_e32 v63, 31, v62
	s_addc_u32 s13, s88, s13
	v_mov_b32_e32 v12, 0x5000
	v_mov_b32_e32 v15, 0
	global_load_dwordx4 v[0:3], v[0:1], off
	s_nop 0
	global_load_dwordx4 v[4:7], v[4:5], off
	v_lshl_add_u64 v[8:9], v[62:63], 4, s[66:67]
	global_load_dword v66, v12, s[12:13]
	v_mov_b32_e32 v12, 0x8000
	s_add_u32 s2, s89, s2
	global_load_dwordx4 v[8:11], v[8:9], off
	s_addc_u32 s3, s90, s3
	global_load_dword v64, v12, s[12:13]
	global_load_dword v68, v15, s[10:11]
	global_load_dword v70, v15, s[2:3]
	s_mul_i32 s3, s62, 0x2080
	s_mul_hi_u32 s2, s62, 0x2080
	s_add_u32 s70, s58, s3
	s_addc_u32 s71, s59, s2
	s_mov_b32 s2, 0xe32943
	v_mul_hi_i32 v12, v190, s2
	v_lshrrev_b32_e32 v16, 31, v12
	v_ashrrev_i32_e32 v17, 1, v12
	v_add_u32_e32 v65, v17, v16
	v_mul_i32_i24_e32 v12, 0x241, v65
	v_sub_u32_e32 v67, v190, v12
	s_movk_i32 s2, 0x1208
	v_cmp_gt_i32_e32 vcc, s2, v190
	v_subrev_u32_e32 v12, 28, v67
	s_movk_i32 s2, 0x202
	v_cmp_gt_u32_e64 s[18:19], s2, v12
	v_readfirstlane_b32 s56, v190
	s_and_b64 s[2:3], vcc, s[18:19]
	v_mov_b32_e32 v14, 0
	v_mov_b32_e32 v13, 0
	v_mov_b32_e32 v12, 0
	v_mov_b32_e32 v84, 0
	s_and_saveexec_b64 s[10:11], s[2:3]
	s_cbranch_execz .LBB0_1189
	v_add3_u32 v14, v17, v16, s50
	v_cmp_lt_i32_e64 s[2:3], 3, v14
	s_and_saveexec_b64 s[12:13], s[2:3]
	s_xor_b64 s[2:3], exec, s[12:13]
	v_add_u32_e32 v12, -4, v14
	s_mov_b32 s12, 0x410000
	v_mov_b64_e32 v[14:15], 0x2040000
	v_mad_u64_u32 v[12:13], s[12:13], v12, s12, v[14:15]
	s_andn2_saveexec_b64 s[2:3], s[2:3]
	s_mov_b32 s12, 0x810000
	v_mad_i64_i32 v[12:13], s[12:13], v14, s12, 0
	s_or_b64 exec, exec, s[2:3]
	v_lshl_add_u64 v[12:13], v[12:13], 1, s[70:71]
	v_lshlrev_b32_e32 v32, 4, v67
	v_lshl_add_u64 v[16:17], v[12:13], 0, v[32:33]
	global_load_dwordx4 v[12:15], v[16:17], off offset:-352
	v_cmp_lt_u32_e64 s[2:3], 28, v67
	v_mov_b32_e32 v19, 0
	v_mov_b32_e32 v18, 0
	s_and_b64 s[2:3], s[2:3], s[92:93]
	s_and_saveexec_b64 s[12:13], s[2:3]
	s_cbranch_execz .LBB0_1186
	global_load_ushort v110, v[16:17], off offset:-354
.LBB0_1186:
	s_or_b64 exec, exec, s[12:13]
	s_movk_i32 s2, 0x21d
	v_cmp_gt_u32_e64 s[2:3], s2, v67
	s_and_b64 s[2:3], s[2:3], s[94:95]
	s_and_saveexec_b64 s[12:13], s[2:3]
	s_cbranch_execz .LBB0_1188
	global_load_ushort v111, v[16:17], off offset:-336

; template <int NQ, int NB, int L>
; __device__ __forceinline__ void conv_unit(LAS unsigned char* lds, const Args& a, int j, int seq0, int c, int tid) {
;     ...
;         for (int it = 0; it < NIT; ++it) {
;             const int idx = it * 512 + tid; const int b = idx / NCH, ch = idx % NCH, p = ch * 8 - PADL;
;             raws[it] = (u32x4){0u, 0u, 0u, 0u}; halos[it] = 0u;
;             if (idx < NB * NCH && p >= 0 && p < L) {
;                 const bf16_t* row = V + seq_off_ch(seq0 + b) + (size_t)c * LS + XPAD + p;
;                 raws[it] = *(const u32x4*)row;
;                 const unsigned xm = p > 0 ? (unsigned)row[-1] : 0u, xp = (p + 8 < L) ? (unsigned)row[8] : 0u;
;                 halos[it] = xm | (xp << 16);
;             }
;         }
.LBB0_1189:
	s_or_b64 exec, exec, s[10:11]
	s_mov_b32 s2, 0xe32943
	v_mul_hi_i32 v16, v191, s2
	v_lshrrev_b32_e32 v20, 31, v16
	v_ashrrev_i32_e32 v21, 1, v16
	v_add_u32_e32 v69, v21, v20
	v_mul_i32_i24_e32 v16, 0x241, v69
	v_sub_u32_e32 v71, v191, v16
	s_movk_i32 s2, 0x1008
	v_subrev_u32_e32 v16, 28, v71
	s_movk_i32 s10, 0x202
	v_cmp_gt_i32_e64 s[2:3], s2, v190
	v_cmp_gt_u32_e64 s[22:23], s10, v16
	s_and_b64 s[10:11], s[2:3], s[22:23]
	v_mov_b32_e32 v19, 0
	v_mov_b32_e32 v18, 0
	v_mov_b32_e32 v17, 0
	v_mov_b32_e32 v16, 0
	v_mov_b32_e32 v87, 0
	s_and_saveexec_b64 s[12:13], s[10:11]
	s_cbranch_execz .LBB0_1199
	v_add3_u32 v18, v21, v20, s50
	v_cmp_lt_i32_e64 s[10:11], 3, v18
	s_and_saveexec_b64 s[14:15], s[10:11]
	s_xor_b64 s[10:11], exec, s[14:15]
	v_add_u32_e32 v16, -4, v18
	s_mov_b32 s14, 0x410000
	v_mov_b64_e32 v[18:19], 0x2040000
	v_mad_u64_u32 v[16:17], s[14:15], v16, s14, v[18:19]
	s_andn2_saveexec_b64 s[10:11], s[10:11]
	s_mov_b32 s14, 0x810000
	v_mad_i64_i32 v[16:17], s[14:15], v18, s14, 0
	s_or_b64 exec, exec, s[10:11]
	v_lshl_add_u64 v[16:17], v[16:17], 1, s[70:71]
	v_lshlrev_b32_e32 v32, 4, v71
	v_lshl_add_u64 v[20:21], v[16:17], 0, v[32:33]
	global_load_dwordx4 v[16:19], v[20:21], off offset:-352
	v_cmp_lt_u32_e64 s[10:11], 28, v71
	v_mov_b32_e32 v23, 0
	v_mov_b32_e32 v22, 0
	s_and_b64 s[10:11], s[10:11], s[92:93]
	s_and_saveexec_b64 s[14:15], s[10:11]
	s_cbranch_execz .LBB0_1196
	global_load_ushort v112, v[20:21], off offset:-354
.LBB0_1196:
	s_or_b64 exec, exec, s[14:15]
	s_movk_i32 s10, 0x21d
	v_cmp_gt_u32_e64 s[10:11], s10, v71
	s_and_b64 s[10:11], s[10:11], s[94:95]
	s_and_saveexec_b64 s[14:15], s[10:11]
	s_cbranch_execz .LBB0_1198
	global_load_ushort v113, v[20:21], off offset:-336

; template <int NQ, int NB, int L>
; __device__ __forceinline__ void conv_unit(LAS unsigned char* lds, const Args& a, int j, int seq0, int c, int tid) {
;     ...
;         for (int it = 0; it < NIT; ++it) {
;             const int idx = it * 512 + tid; const int b = idx / NCH, ch = idx % NCH, p = ch * 8 - PADL;
;             raws[it] = (u32x4){0u, 0u, 0u, 0u}; halos[it] = 0u;
;             if (idx < NB * NCH && p >= 0 && p < L) {
;                 const bf16_t* row = V + seq_off_ch(seq0 + b) + (size_t)c * LS + XPAD + p;
;                 raws[it] = *(const u32x4*)row;
;                 const unsigned xm = p > 0 ? (unsigned)row[-1] : 0u, xp = (p + 8 < L) ? (unsigned)row[8] : 0u;
;                 halos[it] = xm | (xp << 16);
;             }
;         }
.LBB0_1199:
	s_or_b64 exec, exec, s[12:13]
	s_mov_b32 s10, 0xe32943
	v_mul_hi_i32 v20, v192, s10
	v_lshrrev_b32_e32 v24, 31, v20
	v_ashrrev_i32_e32 v25, 1, v20
	v_add_u32_e32 v72, v25, v24
	v_mul_i32_i24_e32 v20, 0x241, v72
	v_sub_u32_e32 v73, v192, v20
	s_movk_i32 s10, 0xe08
	v_subrev_u32_e32 v20, 28, v73
	s_movk_i32 s12, 0x202
	v_cmp_gt_i32_e64 s[10:11], s10, v190
	v_cmp_gt_u32_e64 s[26:27], s12, v20
	s_and_b64 s[12:13], s[10:11], s[26:27]
	v_mov_b32_e32 v23, 0
	v_mov_b32_e32 v22, 0
	v_mov_b32_e32 v21, 0
	v_mov_b32_e32 v20, 0
	v_mov_b32_e32 v90, 0
	s_and_saveexec_b64 s[14:15], s[12:13]
	s_cbranch_execz .LBB0_1209
	v_add3_u32 v22, v25, v24, s50
	v_cmp_lt_i32_e64 s[12:13], 3, v22
	s_and_saveexec_b64 s[16:17], s[12:13]
	s_xor_b64 s[12:13], exec, s[16:17]
	v_add_u32_e32 v20, -4, v22
	s_mov_b32 s16, 0x410000
	v_mov_b64_e32 v[22:23], 0x2040000
	v_mad_u64_u32 v[20:21], s[16:17], v20, s16, v[22:23]
	s_andn2_saveexec_b64 s[12:13], s[12:13]
	s_mov_b32 s16, 0x810000
	v_mad_i64_i32 v[20:21], s[16:17], v22, s16, 0
	s_or_b64 exec, exec, s[12:13]
	v_lshl_add_u64 v[20:21], v[20:21], 1, s[70:71]
	v_lshlrev_b32_e32 v32, 4, v73
	v_lshl_add_u64 v[24:25], v[20:21], 0, v[32:33]
	global_load_dwordx4 v[20:23], v[24:25], off offset:-352
	v_cmp_lt_u32_e64 s[12:13], 28, v73
	v_mov_b32_e32 v27, 0
	v_mov_b32_e32 v26, 0
	s_and_b64 s[12:13], s[12:13], s[92:93]
	s_and_saveexec_b64 s[16:17], s[12:13]
	s_cbranch_execz .LBB0_1206
	global_load_ushort v114, v[24:25], off offset:-354
.LBB0_1206:
	s_or_b64 exec, exec, s[16:17]
	s_movk_i32 s12, 0x21d
	v_cmp_gt_u32_e64 s[12:13], s12, v73
	s_and_b64 s[12:13], s[12:13], s[94:95]
	s_and_saveexec_b64 s[16:17], s[12:13]
	s_cbranch_execz .LBB0_1208
	global_load_ushort v115, v[24:25], off offset:-336

; template <int NQ, int NB, int L>
; __device__ __forceinline__ void conv_unit(LAS unsigned char* lds, const Args& a, int j, int seq0, int c, int tid) {
;     ...
;         for (int it = 0; it < NIT; ++it) {
;             const int idx = it * 512 + tid; const int b = idx / NCH, ch = idx % NCH, p = ch * 8 - PADL;
;             raws[it] = (u32x4){0u, 0u, 0u, 0u}; halos[it] = 0u;
;             if (idx < NB * NCH && p >= 0 && p < L) {
;                 const bf16_t* row = V + seq_off_ch(seq0 + b) + (size_t)c * LS + XPAD + p;
;                 raws[it] = *(const u32x4*)row;
;                 const unsigned xm = p > 0 ? (unsigned)row[-1] : 0u, xp = (p + 8 < L) ? (unsigned)row[8] : 0u;
;                 halos[it] = xm | (xp << 16);
;             }
;         }
.LBB0_1209:
	s_or_b64 exec, exec, s[14:15]
	v_add_u32_e32 v24, 0x600, v190
	s_mov_b32 s12, 0xe32943
	v_mul_hi_i32 v25, v24, s12
	v_lshrrev_b32_e32 v28, 31, v25
	v_ashrrev_i32_e32 v29, 1, v25
	v_add_u32_e32 v74, v29, v28
	v_mul_i32_i24_e32 v25, 0x241, v74
	v_sub_u32_e32 v75, v24, v25
	s_movk_i32 s12, 0xc08
	v_subrev_u32_e32 v24, 28, v75
	s_movk_i32 s14, 0x202
	v_cmp_gt_i32_e64 s[12:13], s12, v190
	v_cmp_gt_u32_e64 s[30:31], s14, v24
	s_and_b64 s[14:15], s[12:13], s[30:31]
	v_mov_b32_e32 v27, 0
	v_mov_b32_e32 v26, 0
	v_mov_b32_e32 v25, 0
	v_mov_b32_e32 v24, 0
	v_mov_b32_e32 v91, 0
	s_and_saveexec_b64 s[16:17], s[14:15]
	s_cbranch_execz .LBB0_1219
	v_add3_u32 v26, v29, v28, s50
	v_cmp_lt_i32_e64 s[14:15], 3, v26
	s_and_saveexec_b64 s[20:21], s[14:15]
	s_xor_b64 s[14:15], exec, s[20:21]
	v_add_u32_e32 v24, -4, v26
	s_mov_b32 s20, 0x410000
	v_mov_b64_e32 v[26:27], 0x2040000
	v_mad_u64_u32 v[24:25], s[20:21], v24, s20, v[26:27]
	s_andn2_saveexec_b64 s[14:15], s[14:15]
	s_mov_b32 s20, 0x810000
	v_mad_i64_i32 v[24:25], s[20:21], v26, s20, 0
	s_or_b64 exec, exec, s[14:15]
	v_lshl_add_u64 v[24:25], v[24:25], 1, s[70:71]
	v_lshlrev_b32_e32 v32, 4, v75
	v_lshl_add_u64 v[28:29], v[24:25], 0, v[32:33]
	global_load_dwordx4 v[24:27], v[28:29], off offset:-352
	v_cmp_lt_u32_e64 s[14:15], 28, v75
	v_mov_b32_e32 v31, 0
	v_mov_b32_e32 v30, 0
	s_and_b64 s[14:15], s[14:15], s[92:93]
	s_and_saveexec_b64 s[20:21], s[14:15]
	s_cbranch_execz .LBB0_1216
	global_load_ushort v116, v[28:29], off offset:-354
.LBB0_1216:
	s_or_b64 exec, exec, s[20:21]
	s_movk_i32 s14, 0x21d
	v_cmp_gt_u32_e64 s[14:15], s14, v75
	s_and_b64 s[14:15], s[14:15], s[94:95]
	s_and_saveexec_b64 s[20:21], s[14:15]
	s_cbranch_execz .LBB0_1218
	global_load_ushort v117, v[28:29], off offset:-336

; template <int NQ, int NB, int L>
; __device__ __forceinline__ void conv_unit(LAS unsigned char* lds, const Args& a, int j, int seq0, int c, int tid) {
;     ...
;         for (int it = 0; it < NIT; ++it) {
;             const int idx = it * 512 + tid; const int b = idx / NCH, ch = idx % NCH, p = ch * 8 - PADL;
;             raws[it] = (u32x4){0u, 0u, 0u, 0u}; halos[it] = 0u;
;             if (idx < NB * NCH && p >= 0 && p < L) {
;                 const bf16_t* row = V + seq_off_ch(seq0 + b) + (size_t)c * LS + XPAD + p;
;                 raws[it] = *(const u32x4*)row;
;                 const unsigned xm = p > 0 ? (unsigned)row[-1] : 0u, xp = (p + 8 < L) ? (unsigned)row[8] : 0u;
;                 halos[it] = xm | (xp << 16);
;             }
;         }
.LBB0_1219:
	s_or_b64 exec, exec, s[16:17]
	v_add_u32_e32 v28, 0x800, v190
	s_mov_b32 s14, 0xe32943
	v_mul_hi_i32 v29, v28, s14
	v_lshrrev_b32_e32 v32, 31, v29
	v_ashrrev_i32_e32 v34, 1, v29
	v_add_u32_e32 v76, v34, v32
	v_mul_i32_i24_e32 v29, 0x241, v76
	v_sub_u32_e32 v77, v28, v29
	s_movk_i32 s14, 0xa08
	v_subrev_u32_e32 v28, 28, v77
	s_movk_i32 s16, 0x202
	v_cmp_gt_i32_e64 s[14:15], s14, v190
	v_cmp_gt_u32_e64 s[36:37], s16, v28
	s_and_b64 s[16:17], s[14:15], s[36:37]
	v_mov_b32_e32 v31, 0
	v_mov_b32_e32 v30, 0
	v_mov_b32_e32 v29, 0
	v_mov_b32_e32 v28, 0
	v_mov_b32_e32 v92, 0
	s_and_saveexec_b64 s[20:21], s[16:17]
	s_cbranch_execz .LBB0_1229
	v_add3_u32 v30, v34, v32, s50
	v_cmp_lt_i32_e64 s[16:17], 3, v30
	s_and_saveexec_b64 s[24:25], s[16:17]
	s_xor_b64 s[16:17], exec, s[24:25]
	v_add_u32_e32 v28, -4, v30
	s_mov_b32 s24, 0x410000
	v_mov_b64_e32 v[30:31], 0x2040000
	v_mad_u64_u32 v[28:29], s[24:25], v28, s24, v[30:31]
	s_andn2_saveexec_b64 s[16:17], s[16:17]
	s_mov_b32 s24, 0x810000
	v_mad_i64_i32 v[28:29], s[24:25], v30, s24, 0
	s_or_b64 exec, exec, s[16:17]
	v_lshl_add_u64 v[28:29], v[28:29], 1, s[70:71]
	v_lshlrev_b32_e32 v32, 4, v77
	v_lshl_add_u64 v[34:35], v[28:29], 0, v[32:33]
	global_load_dwordx4 v[28:31], v[34:35], off offset:-352
	v_cmp_lt_u32_e64 s[16:17], 28, v77
	v_mov_b32_e32 v36, 0
	v_mov_b32_e32 v32, 0
	s_and_b64 s[16:17], s[16:17], s[92:93]
	s_and_saveexec_b64 s[24:25], s[16:17]
	s_cbranch_execz .LBB0_1226
	global_load_ushort v118, v[34:35], off offset:-354
.LBB0_1226:
	s_or_b64 exec, exec, s[24:25]
	s_movk_i32 s16, 0x21d
	v_cmp_gt_u32_e64 s[16:17], s16, v77
	s_and_b64 s[16:17], s[16:17], s[94:95]
	s_and_saveexec_b64 s[24:25], s[16:17]
	s_cbranch_execz .LBB0_1228
	global_load_ushort v119, v[34:35], off offset:-336

; template <int NQ, int NB, int L>
; __device__ __forceinline__ void conv_unit(LAS unsigned char* lds, const Args& a, int j, int seq0, int c, int tid) {
;     ...
;         for (int it = 0; it < NIT; ++it) {
;             const int idx = it * 512 + tid; const int b = idx / NCH, ch = idx % NCH, p = ch * 8 - PADL;
;             raws[it] = (u32x4){0u, 0u, 0u, 0u}; halos[it] = 0u;
;             if (idx < NB * NCH && p >= 0 && p < L) {
;                 const bf16_t* row = V + seq_off_ch(seq0 + b) + (size_t)c * LS + XPAD + p;
;                 raws[it] = *(const u32x4*)row;
;                 const unsigned xm = p > 0 ? (unsigned)row[-1] : 0u, xp = (p + 8 < L) ? (unsigned)row[8] : 0u;
;                 halos[it] = xm | (xp << 16);
;             }
;         }
.LBB0_1229:
	s_or_b64 exec, exec, s[20:21]
	v_add_u32_e32 v34, 0xa00, v190
	s_mov_b32 s16, 0xe32943
	v_mul_hi_i32 v35, v34, s16
	v_lshrrev_b32_e32 v32, 31, v35
	v_ashrrev_i32_e32 v38, 1, v35
	v_add_u32_e32 v78, v38, v32
	v_mul_i32_i24_e32 v35, 0x241, v78
	v_sub_u32_e32 v79, v34, v35
	s_movk_i32 s16, 0x808
	v_subrev_u32_e32 v34, 28, v79
	s_movk_i32 s20, 0x202
	v_cmp_gt_i32_e64 s[16:17], s16, v190
	v_cmp_gt_u32_e64 s[38:39], s20, v34
	s_and_b64 s[20:21], s[16:17], s[38:39]
	v_mov_b32_e32 v37, 0
	v_mov_b32_e32 v36, 0
	v_mov_b32_e32 v35, 0
	v_mov_b32_e32 v34, 0
	v_mov_b32_e32 v93, 0
	s_and_saveexec_b64 s[24:25], s[20:21]
	s_cbranch_execz .LBB0_1239
	v_add3_u32 v32, v38, v32, s50
	v_cmp_lt_i32_e64 s[20:21], 3, v32
	s_and_saveexec_b64 s[28:29], s[20:21]
	s_xor_b64 s[20:21], exec, s[28:29]
	v_add_u32_e32 v32, -4, v32
	s_mov_b32 s28, 0x410000
	v_mov_b64_e32 v[34:35], 0x2040000
	v_mad_u64_u32 v[34:35], s[28:29], v32, s28, v[34:35]
	s_andn2_saveexec_b64 s[20:21], s[20:21]
	s_mov_b32 s28, 0x810000
	v_mad_i64_i32 v[34:35], s[28:29], v32, s28, 0
	s_or_b64 exec, exec, s[20:21]
	v_lshl_add_u64 v[34:35], v[34:35], 1, s[70:71]
	v_lshlrev_b32_e32 v32, 4, v79
	v_lshl_add_u64 v[38:39], v[34:35], 0, v[32:33]
	global_load_dwordx4 v[34:37], v[38:39], off offset:-352
	v_cmp_lt_u32_e64 s[20:21], 28, v79
	v_mov_b32_e32 v40, 0
	v_mov_b32_e32 v32, 0
	s_and_b64 s[20:21], s[20:21], s[92:93]
	s_and_saveexec_b64 s[28:29], s[20:21]
	s_cbranch_execz .LBB0_1236
	global_load_ushort v120, v[38:39], off offset:-354
.LBB0_1236:
	s_or_b64 exec, exec, s[28:29]
	s_movk_i32 s20, 0x21d
	v_cmp_gt_u32_e64 s[20:21], s20, v79
	s_and_b64 s[20:21], s[20:21], s[94:95]
	s_and_saveexec_b64 s[28:29], s[20:21]
	s_cbranch_execz .LBB0_1238
	global_load_ushort v121, v[38:39], off offset:-336

; template <int NQ, int NB, int L>
; __device__ __forceinline__ void conv_unit(LAS unsigned char* lds, const Args& a, int j, int seq0, int c, int tid) {
;     ...
;         for (int it = 0; it < NIT; ++it) {
;             const int idx = it * 512 + tid; const int b = idx / NCH, ch = idx % NCH, p = ch * 8 - PADL;
;             raws[it] = (u32x4){0u, 0u, 0u, 0u}; halos[it] = 0u;
;             if (idx < NB * NCH && p >= 0 && p < L) {
;                 const bf16_t* row = V + seq_off_ch(seq0 + b) + (size_t)c * LS + XPAD + p;
;                 raws[it] = *(const u32x4*)row;
;                 const unsigned xm = p > 0 ? (unsigned)row[-1] : 0u, xp = (p + 8 < L) ? (unsigned)row[8] : 0u;
;                 halos[it] = xm | (xp << 16);
;             }
;         }
.LBB0_1239:
	s_or_b64 exec, exec, s[24:25]
	v_add_u32_e32 v38, 0xc00, v190
	s_mov_b32 s20, 0xe32943
	v_mul_hi_i32 v39, v38, s20
	v_lshrrev_b32_e32 v32, 31, v39
	v_ashrrev_i32_e32 v42, 1, v39
	v_add_u32_e32 v80, v42, v32
	v_mul_i32_i24_e32 v39, 0x241, v80
	v_sub_u32_e32 v81, v38, v39
	s_movk_i32 s20, 0x608
	v_subrev_u32_e32 v38, 28, v81
	s_movk_i32 s24, 0x202
	v_cmp_gt_i32_e64 s[20:21], s20, v190
	v_cmp_gt_u32_e64 s[40:41], s24, v38
	s_and_b64 s[24:25], s[20:21], s[40:41]
	v_mov_b32_e32 v41, 0
	v_mov_b32_e32 v40, 0
	v_mov_b32_e32 v39, 0
	v_mov_b32_e32 v38, 0
	v_mov_b32_e32 v94, 0
	s_and_saveexec_b64 s[28:29], s[24:25]
	s_cbranch_execz .LBB0_1249
	v_add3_u32 v32, v42, v32, s50
	v_cmp_lt_i32_e64 s[24:25], 3, v32
	s_and_saveexec_b64 s[34:35], s[24:25]
	s_xor_b64 s[24:25], exec, s[34:35]
	v_add_u32_e32 v32, -4, v32
	s_mov_b32 s34, 0x410000
	v_mov_b64_e32 v[38:39], 0x2040000
	v_mad_u64_u32 v[38:39], s[34:35], v32, s34, v[38:39]
	s_andn2_saveexec_b64 s[24:25], s[24:25]
	s_mov_b32 s34, 0x810000
	v_mad_i64_i32 v[38:39], s[34:35], v32, s34, 0
	s_or_b64 exec, exec, s[24:25]
	v_lshl_add_u64 v[38:39], v[38:39], 1, s[70:71]
	v_lshlrev_b32_e32 v32, 4, v81
	v_lshl_add_u64 v[42:43], v[38:39], 0, v[32:33]
	global_load_dwordx4 v[38:41], v[42:43], off offset:-352
	v_cmp_lt_u32_e64 s[24:25], 28, v81
	v_mov_b32_e32 v44, 0
	v_mov_b32_e32 v32, 0
	s_and_b64 s[24:25], s[24:25], s[92:93]
	s_and_saveexec_b64 s[34:35], s[24:25]
	s_cbranch_execz .LBB0_1246
	global_load_ushort v122, v[42:43], off offset:-354
.LBB0_1246:
	s_or_b64 exec, exec, s[34:35]
	s_movk_i32 s24, 0x21d
	v_cmp_gt_u32_e64 s[24:25], s24, v81
	s_and_b64 s[24:25], s[24:25], s[94:95]
	s_and_saveexec_b64 s[34:35], s[24:25]
	s_cbranch_execz .LBB0_1248
	global_load_ushort v123, v[42:43], off offset:-336

; template <int NQ, int NB, int L>
; __device__ __forceinline__ void conv_unit(LAS unsigned char* lds, const Args& a, int j, int seq0, int c, int tid) {
;     ...
;         for (int it = 0; it < NIT; ++it) {
;             const int idx = it * 512 + tid; const int b = idx / NCH, ch = idx % NCH, p = ch * 8 - PADL;
;             raws[it] = (u32x4){0u, 0u, 0u, 0u}; halos[it] = 0u;
;             if (idx < NB * NCH && p >= 0 && p < L) {
;                 const bf16_t* row = V + seq_off_ch(seq0 + b) + (size_t)c * LS + XPAD + p;
;                 raws[it] = *(const u32x4*)row;
;                 const unsigned xm = p > 0 ? (unsigned)row[-1] : 0u, xp = (p + 8 < L) ? (unsigned)row[8] : 0u;
;                 halos[it] = xm | (xp << 16);
;             }
;         }
.LBB0_1249:
	s_or_b64 exec, exec, s[28:29]
	v_add_u32_e32 v42, 0xe00, v190
	s_mov_b32 s24, 0xe32943
	v_mul_hi_i32 v43, v42, s24
	v_lshrrev_b32_e32 v32, 31, v43
	v_ashrrev_i32_e32 v46, 1, v43
	v_add_u32_e32 v82, v46, v32
	v_mul_i32_i24_e32 v43, 0x241, v82
	v_sub_u32_e32 v83, v42, v43
	s_movk_i32 s24, 0x408
	v_subrev_u32_e32 v42, 28, v83
	s_movk_i32 s28, 0x202
	v_cmp_gt_i32_e64 s[24:25], s24, v190
	v_cmp_gt_u32_e64 s[42:43], s28, v42
	s_and_b64 s[28:29], s[24:25], s[42:43]
	v_mov_b32_e32 v45, 0
	v_mov_b32_e32 v44, 0
	v_mov_b32_e32 v43, 0
	v_mov_b32_e32 v42, 0
	v_mov_b32_e32 v95, 0
	s_and_saveexec_b64 s[34:35], s[28:29]
	s_cbranch_execz .LBB0_1259
	v_add3_u32 v32, v46, v32, s50
	v_cmp_lt_i32_e64 s[28:29], 3, v32
	s_and_saveexec_b64 s[44:45], s[28:29]
	s_xor_b64 s[28:29], exec, s[44:45]
	v_add_u32_e32 v32, -4, v32
	s_mov_b32 s44, 0x410000
	v_mov_b64_e32 v[42:43], 0x2040000
	v_mad_u64_u32 v[42:43], s[44:45], v32, s44, v[42:43]
	s_andn2_saveexec_b64 s[28:29], s[28:29]
	s_mov_b32 s44, 0x810000
	v_mad_i64_i32 v[42:43], s[44:45], v32, s44, 0
	s_or_b64 exec, exec, s[28:29]
	v_lshl_add_u64 v[42:43], v[42:43], 1, s[70:71]
	v_lshlrev_b32_e32 v32, 4, v83
	v_lshl_add_u64 v[46:47], v[42:43], 0, v[32:33]
	global_load_dwordx4 v[42:45], v[46:47], off offset:-352
	v_cmp_lt_u32_e64 s[28:29], 28, v83
	v_mov_b32_e32 v48, 0
	v_mov_b32_e32 v32, 0
	s_and_b64 s[28:29], s[28:29], s[92:93]
	s_and_saveexec_b64 s[44:45], s[28:29]
	s_cbranch_execz .LBB0_1256
	global_load_ushort v124, v[46:47], off offset:-354
.LBB0_1256:
	s_or_b64 exec, exec, s[44:45]
	s_movk_i32 s28, 0x21d
	v_cmp_gt_u32_e64 s[28:29], s28, v83
	s_and_b64 s[28:29], s[28:29], s[94:95]
	s_and_saveexec_b64 s[44:45], s[28:29]
	s_cbranch_execz .LBB0_1258
	global_load_ushort v125, v[46:47], off offset:-336

; template <int NQ, int NB, int L>
; __device__ __forceinline__ void conv_unit(LAS unsigned char* lds, const Args& a, int j, int seq0, int c, int tid) {
;     ...
;         for (int it = 0; it < NIT; ++it) {
;             const int idx = it * 512 + tid; const int b = idx / NCH, ch = idx % NCH, p = ch * 8 - PADL;
;             raws[it] = (u32x4){0u, 0u, 0u, 0u}; halos[it] = 0u;
;             if (idx < NB * NCH && p >= 0 && p < L) {
;                 const bf16_t* row = V + seq_off_ch(seq0 + b) + (size_t)c * LS + XPAD + p;
;                 raws[it] = *(const u32x4*)row;
;                 const unsigned xm = p > 0 ? (unsigned)row[-1] : 0u, xp = (p + 8 < L) ? (unsigned)row[8] : 0u;
;                 halos[it] = xm | (xp << 16);
;             }
;         }
.LBB0_1259:
	s_or_b64 exec, exec, s[34:35]
	v_add_u32_e32 v46, 0x1000, v190
	s_mov_b32 s28, 0xe32943
	v_mul_hi_i32 v47, v46, s28
	v_lshrrev_b32_e32 v32, 31, v47
	v_ashrrev_i32_e32 v50, 1, v47
	v_add_u32_e32 v85, v50, v32
	v_mul_i32_i24_e32 v47, 0x241, v85
	v_sub_u32_e32 v86, v46, v47
	s_movk_i32 s28, 0x208
	v_subrev_u32_e32 v46, 28, v86
	s_movk_i32 s34, 0x202
	v_cmp_gt_i32_e64 s[28:29], s28, v190
	v_cmp_gt_u32_e64 s[44:45], s34, v46
	s_and_b64 s[34:35], s[28:29], s[44:45]
	v_mov_b32_e32 v49, 0
	v_mov_b32_e32 v48, 0
	v_mov_b32_e32 v47, 0
	v_mov_b32_e32 v46, 0
	v_mov_b32_e32 v96, 0
	s_and_saveexec_b64 s[46:47], s[34:35]
	s_cbranch_execz .LBB0_1269
	v_add3_u32 v32, v50, v32, s50
	v_cmp_lt_i32_e64 s[34:35], 3, v32
	s_and_saveexec_b64 s[48:49], s[34:35]
	s_xor_b64 s[34:35], exec, s[48:49]
	v_add_u32_e32 v32, -4, v32
	s_mov_b32 s48, 0x410000
	v_mov_b64_e32 v[46:47], 0x2040000
	v_mad_u64_u32 v[46:47], s[48:49], v32, s48, v[46:47]
	s_andn2_saveexec_b64 s[34:35], s[34:35]
	s_mov_b32 s48, 0x810000
	v_mad_i64_i32 v[46:47], s[48:49], v32, s48, 0
	s_or_b64 exec, exec, s[34:35]
	v_lshl_add_u64 v[46:47], v[46:47], 1, s[70:71]
	v_lshlrev_b32_e32 v32, 4, v86
	v_lshl_add_u64 v[50:51], v[46:47], 0, v[32:33]
	global_load_dwordx4 v[46:49], v[50:51], off offset:-352
	v_cmp_lt_u32_e64 s[34:35], 28, v86
	v_mov_b32_e32 v52, 0
	v_mov_b32_e32 v32, 0
	s_and_b64 s[34:35], s[34:35], s[92:93]
	s_and_saveexec_b64 s[48:49], s[34:35]
	s_cbranch_execz .LBB0_1266
	global_load_ushort v126, v[50:51], off offset:-354
.LBB0_1266:
	s_or_b64 exec, exec, s[48:49]
	s_movk_i32 s34, 0x21d
	v_cmp_gt_u32_e64 s[34:35], s34, v86
	s_and_b64 s[34:35], s[34:35], s[94:95]
	s_and_saveexec_b64 s[48:49], s[34:35]
	s_cbranch_execz .LBB0_1268
	global_load_ushort v127, v[50:51], off offset:-336

; template <int NQ, int NB, int L>
; __device__ __forceinline__ void conv_unit(LAS unsigned char* lds, const Args& a, int j, int seq0, int c, int tid) {
;     ...
;         for (int it = 0; it < NIT; ++it) {
;             const int idx = it * 512 + tid; const int b = idx / NCH, ch = idx % NCH, p = ch * 8 - PADL;
;             raws[it] = (u32x4){0u, 0u, 0u, 0u}; halos[it] = 0u;
;             if (idx < NB * NCH && p >= 0 && p < L) {
;                 const bf16_t* row = V + seq_off_ch(seq0 + b) + (size_t)c * LS + XPAD + p;
;                 raws[it] = *(const u32x4*)row;
;                 const unsigned xm = p > 0 ? (unsigned)row[-1] : 0u, xp = (p + 8 < L) ? (unsigned)row[8] : 0u;
;                 halos[it] = xm | (xp << 16);
;             }
;         }
.LBB0_1269:
	s_or_b64 exec, exec, s[46:47]
	v_add_u32_e32 v32, 0x1200, v190
	s_mov_b32 s34, 0xe32943
	v_mul_hi_i32 v50, v32, s34
	v_lshrrev_b32_e32 v54, 31, v50
	v_ashrrev_i32_e32 v55, 1, v50
	v_add_u32_e32 v88, v55, v54
	v_mul_i32_i24_e32 v50, 0x241, v88
	v_sub_u32_e32 v89, v32, v50
	v_subrev_u32_e32 v32, 28, v89
	s_movk_i32 s46, 0x202
	v_cmp_gt_i32_e64 s[34:35], 8, v190
	v_cmp_gt_u32_e64 s[46:47], s46, v32
	s_and_b64 s[48:49], s[34:35], s[46:47]
	v_mov_b32_e32 v53, 0
	v_mov_b32_e32 v52, 0
	v_mov_b32_e32 v51, 0
	v_mov_b32_e32 v50, 0
	v_mov_b32_e32 v32, 0
	s_and_saveexec_b64 s[72:73], s[48:49]
	s_cbranch_execz .LBB0_1279
	v_add3_u32 v32, v55, v54, s50
	v_cmp_lt_i32_e64 s[48:49], 3, v32
	s_and_saveexec_b64 s[50:51], s[48:49]
	s_xor_b64 s[48:49], exec, s[50:51]
	v_add_u32_e32 v32, -4, v32
	s_mov_b32 s50, 0x410000
	v_mov_b64_e32 v[50:51], 0x2040000
	v_mad_u64_u32 v[50:51], s[50:51], v32, s50, v[50:51]
	s_andn2_saveexec_b64 s[48:49], s[48:49]
	s_mov_b32 s50, 0x810000
	v_mad_i64_i32 v[50:51], s[50:51], v32, s50, 0
	s_or_b64 exec, exec, s[48:49]
	v_lshl_add_u64 v[50:51], v[50:51], 1, s[70:71]
	v_lshlrev_b32_e32 v32, 4, v89
	v_lshl_add_u64 v[54:55], v[50:51], 0, v[32:33]
	global_load_dwordx4 v[50:53], v[54:55], off offset:-352
	v_cmp_lt_u32_e64 s[48:49], 28, v89
	v_mov_b32_e32 v56, 0
	v_mov_b32_e32 v32, 0
	s_and_b64 s[48:49], s[48:49], s[92:93]
	s_and_saveexec_b64 s[70:71], s[48:49]
	s_cbranch_execz .LBB0_1276
	global_load_ushort v128, v[54:55], off offset:-354
.LBB0_1276:
	s_or_b64 exec, exec, s[70:71]
	s_movk_i32 s48, 0x21d
	v_cmp_gt_u32_e64 s[48:49], s48, v89
	s_and_b64 s[48:49], s[48:49], s[94:95]
	s_and_saveexec_b64 s[70:71], s[48:49]
	s_cbranch_execz .LBB0_1278
	global_load_ushort v129, v[54:55], off offset:-336

; __device__ __forceinline__ unsigned cvtpk(float lo, float hi) { f32x2 v = {lo, hi}; bf16x2_t b = __builtin_convertvector(v, bf16x2_t); return __builtin_bit_cast(unsigned, b); }
; template <int NQ, int NB, int L>
; __device__ __forceinline__ void conv_unit(LAS unsigned char* lds, const Args& a, int j, int seq0, int c, int tid) {
;     ...
;         for (int it = 0; it < NIT; ++it) {
;             const int idx = it * 512 + tid; const int b = idx / NCH, ch = idx % NCH, p = ch * 8 - PADL;
;             u32x4 o = {0u, 0u, 0u, 0u};
;             if (p >= 0 && p < L) {
;                 const u32x4 raw = raws[it];
;                 float x[10];
;                 x[0] = bflo(halos[it]); x[9] = bfhi(halos[it]);
;                 x[1] = bflo(raw.x); x[2] = bfhi(raw.x); x[3] = bflo(raw.y); x[4] = bfhi(raw.y); x[5] = bflo(raw.z); x[6] = bfhi(raw.z); x[7] = bflo(raw.w); x[8] = bfhi(raw.w);
;                 float y[8];
; #pragma unroll
;                 for (int i = 0; i < 8; ++i) y[i] = w0 * x[i] + w1 * x[i + 1] + w2 * x[i + 2] + bb;
;                 o.x = cvtpk(y[0], y[1]); o.y = cvtpk(y[2], y[3]); o.z = cvtpk(y[4], y[5]); o.w = cvtpk(y[6], y[7]);
.LBB0_1279:
	s_or_b64 exec, exec, s[72:73]
	s_waitcnt vmcnt(0)
	v_mov_b32_dpp v140, v15 wave_shr:1 row_mask:0xf bank_mask:0xf bound_ctrl:0
	v_mov_b32_dpp v141, v12 wave_shl:1 row_mask:0xf bank_mask:0xf bound_ctrl:0
	v_lshrrev_b32_e32 v140, 16, v140
	v_and_b32_e32 v141, 0xffff, v141
	v_or_b32_e32 v110, v110, v140
	v_or_b32_e32 v111, v111, v141
	v_lshl_or_b32 v84, v111, 16, v110
	v_mov_b32_dpp v140, v19 wave_shr:1 row_mask:0xf bank_mask:0xf bound_ctrl:0
	v_mov_b32_dpp v141, v16 wave_shl:1 row_mask:0xf bank_mask:0xf bound_ctrl:0
	v_lshrrev_b32_e32 v140, 16, v140
	v_and_b32_e32 v141, 0xffff, v141
	v_or_b32_e32 v112, v112, v140
	v_or_b32_e32 v113, v113, v141
	v_lshl_or_b32 v87, v113, 16, v112
	v_mov_b32_dpp v140, v23 wave_shr:1 row_mask:0xf bank_mask:0xf bound_ctrl:0
	v_mov_b32_dpp v141, v20 wave_shl:1 row_mask:0xf bank_mask:0xf bound_ctrl:0
	v_lshrrev_b32_e32 v140, 16, v140
	v_and_b32_e32 v141, 0xffff, v141
	v_or_b32_e32 v114, v114, v140
	v_or_b32_e32 v115, v115, v141
	v_lshl_or_b32 v90, v115, 16, v114
	v_mov_b32_dpp v140, v27 wave_shr:1 row_mask:0xf bank_mask:0xf bound_ctrl:0
	v_mov_b32_dpp v141, v24 wave_shl:1 row_mask:0xf bank_mask:0xf bound_ctrl:0
	v_lshrrev_b32_e32 v140, 16, v140
	v_and_b32_e32 v141, 0xffff, v141
	v_or_b32_e32 v116, v116, v140
	v_or_b32_e32 v117, v117, v141
	v_lshl_or_b32 v91, v117, 16, v116
	v_mov_b32_dpp v140, v31 wave_shr:1 row_mask:0xf bank_mask:0xf bound_ctrl:0
	v_mov_b32_dpp v141, v28 wave_shl:1 row_mask:0xf bank_mask:0xf bound_ctrl:0
	v_lshrrev_b32_e32 v140, 16, v140
	v_and_b32_e32 v141, 0xffff, v141
	v_or_b32_e32 v118, v118, v140
	v_or_b32_e32 v119, v119, v141
	v_lshl_or_b32 v92, v119, 16, v118
	v_mov_b32_dpp v140, v37 wave_shr:1 row_mask:0xf bank_mask:0xf bound_ctrl:0
	v_mov_b32_dpp v141, v34 wave_shl:1 row_mask:0xf bank_mask:0xf bound_ctrl:0
	v_lshrrev_b32_e32 v140, 16, v140
	v_and_b32_e32 v141, 0xffff, v141
	v_or_b32_e32 v120, v120, v140
	v_or_b32_e32 v121, v121, v141
	v_lshl_or_b32 v93, v121, 16, v120
	v_mov_b32_dpp v140, v41 wave_shr:1 row_mask:0xf bank_mask:0xf bound_ctrl:0
	v_mov_b32_dpp v141, v38 wave_shl:1 row_mask:0xf bank_mask:0xf bound_ctrl:0
	v_lshrrev_b32_e32 v140, 16, v140
	v_and_b32_e32 v141, 0xffff, v141
	v_or_b32_e32 v122, v122, v140
	v_or_b32_e32 v123, v123, v141
	v_lshl_or_b32 v94, v123, 16, v122
	v_mov_b32_dpp v140, v45 wave_shr:1 row_mask:0xf bank_mask:0xf bound_ctrl:0
	v_mov_b32_dpp v141, v42 wave_shl:1 row_mask:0xf bank_mask:0xf bound_ctrl:0
	v_lshrrev_b32_e32 v140, 16, v140
	v_and_b32_e32 v141, 0xffff, v141
	v_or_b32_e32 v124, v124, v140
	v_or_b32_e32 v125, v125, v141
	v_lshl_or_b32 v95, v125, 16, v124
	v_mov_b32_dpp v140, v49 wave_shr:1 row_mask:0xf bank_mask:0xf bound_ctrl:0
	v_mov_b32_dpp v141, v46 wave_shl:1 row_mask:0xf bank_mask:0xf bound_ctrl:0
	v_lshrrev_b32_e32 v140, 16, v140
	v_and_b32_e32 v141, 0xffff, v141
	v_or_b32_e32 v126, v126, v140
	v_or_b32_e32 v127, v127, v141
	v_lshl_or_b32 v96, v127, 16, v126
	v_mov_b32_dpp v140, v53 wave_shr:1 row_mask:0xf bank_mask:0xf bound_ctrl:0
	v_mov_b32_dpp v141, v50 wave_shl:1 row_mask:0xf bank_mask:0xf bound_ctrl:0
	v_lshrrev_b32_e32 v140, 16, v140
	v_and_b32_e32 v141, 0xffff, v141
	v_or_b32_e32 v128, v128, v140
	v_or_b32_e32 v129, v129, v141
	v_lshl_or_b32 v32, v129, 16, v128
	v_mov_b32_e32 v54, 0
	v_mov_b32_e32 v55, 0
	v_mov_b32_e32 v56, 0
	v_mov_b32_e32 v57, 0
	s_and_saveexec_b64 s[48:49], s[18:19]
	s_cbranch_execz .LBB0_1281
	v_and_b32_e32 v104, 0xffff0000, v12
	v_and_b32_e32 v103, 16, v14
	v_and_b32_e32 v102, 0xffff0000, v13
	v_lshlrev_b32_e32 v107, 16, v13
	v_mov_b32_e32 v106, v104
	v_and_b32_e32 v55, 16, v15
	v_and_b32_e32 v54, 0xffff0000, v14
	v_lshlrev_b32_e32 v57, 16, v15
	v_and_b32_e32 v98, 0xffff0000, v15
	v_lshlrev_b32_e32 v15, 16, v14
	v_mov_b32_e32 v14, v102
	v_pk_mov_b32 v[102:103], v[106:107], v[102:103] op_sel:[1,0]
	v_mov_b32_e32 v56, v54
	v_and_b32_e32 v99, 0xffff0000, v84
	v_and_b32_e32 v105, 16, v13
	v_lshlrev_b32_e32 v13, 16, v12
	v_lshlrev_b32_e32 v12, 16, v84
	s_waitcnt vmcnt(4)
	v_pk_mul_f32 v[102:103], v[66:67], v[102:103] op_sel_hi:[0,1]
	v_pk_mov_b32 v[54:55], v[14:15], v[54:55] op_sel:[1,0]
	v_pk_mov_b32 v[100:101], v[56:57], v[98:99] op_sel:[1,0]
	v_pk_mov_b32 v[104:105], v[12:13], v[104:105] op_sel:[1,0]
	s_waitcnt vmcnt(1)
	v_pk_fma_f32 v[102:103], v[68:69], v[106:107], v[102:103] op_sel_hi:[0,1,1]
	v_pk_mul_f32 v[54:55], v[66:67], v[54:55] op_sel_hi:[0,1]
	v_pk_mul_f32 v[104:105], v[66:67], v[104:105] op_sel_hi:[0,1]
	v_pk_fma_f32 v[102:103], v[64:65], v[14:15], v[102:103] op_sel_hi:[0,1,1]
	v_pk_fma_f32 v[14:15], v[68:69], v[14:15], v[54:55] op_sel_hi:[0,1,1]
	v_pk_mul_f32 v[54:55], v[66:67], v[100:101] op_sel_hi:[0,1]
	v_pk_fma_f32 v[12:13], v[68:69], v[12:13], v[104:105] op_sel_hi:[0,1,1]
	v_pk_fma_f32 v[54:55], v[68:69], v[56:57], v[54:55] op_sel_hi:[0,1,1]
	v_pk_fma_f32 v[12:13], v[64:65], v[106:107], v[12:13] op_sel_hi:[0,1,1]
	v_pk_fma_f32 v[14:15], v[64:65], v[56:57], v[14:15] op_sel_hi:[0,1,1]
	v_pk_fma_f32 v[54:55], v[64:65], v[98:99], v[54:55] op_sel_hi:[0,1,1]
	s_waitcnt vmcnt(0)
	v_pk_add_f32 v[12:13], v[70:71], v[12:13] op_sel_hi:[0,1]
	v_pk_add_f32 v[102:103], v[70:71], v[102:103] op_sel_hi:[0,1]
	v_pk_add_f32 v[14:15], v[70:71], v[14:15] op_sel_hi:[0,1]
	v_pk_add_f32 v[98:99], v[70:71], v[54:55] op_sel_hi:[0,1]
	v_cvt_pk_bf16_f32 v54, v12, v13
	v_cvt_pk_bf16_f32 v55, v102, v103
	v_cvt_pk_bf16_f32 v56, v14, v15
	v_cvt_pk_bf16_f32 v57, v98, v99

; template <int NQ, int NB, int L>
; __device__ __forceinline__ void conv_unit(LAS unsigned char* lds, const Args& a, int j, int seq0, int c, int tid) {
;     ...
;     constexpr int NF = (LEN / 8 + 511) / 512;
;     u32x4 fkr[NF];
;     {
;         const u32x4* src = (const u32x4*)(FK + (size_t)c * LEN);
; #pragma unroll
;         for (int it = 0; it < NF; ++it) { const int i = it * 512 + tid; fkr[it] = src[i < LEN / 8 ? i : 0]; }
;     }
;     {
;         const float w0 = cw[2048 + c], w1 = cw[3072 + 2048 + c], w2 = cw[2 * 3072 + 2048 + c], bb = cb[2048 + c];
;         constexpr int NCH = LPD / 8, NIT = (NB * NCH + 511) / 512;
;         u32x4 raws[NIT]; unsigned halos[NIT];
; #pragma unroll
;         for (int it = 0; it < NIT; ++it) {
;             const int idx = it * 512 + tid; const int b = idx / NCH, ch = idx % NCH, p = ch * 8 - PADL;
;             raws[it] = (u32x4){0u, 0u, 0u, 0u}; halos[it] = 0u;
;             if (idx < NB * NCH && p >= 0 && p < L) {
;                 const bf16_t* row = V + seq_off_ch(seq0 + b) + (size_t)c * LS + XPAD + p;
;                 raws[it] = *(const u32x4*)row;
;                 const unsigned xm = p > 0 ? (unsigned)row[-1] : 0u, xp = (p + 8 < L) ? (unsigned)row[8] : 0u;
;                 halos[it] = xm | (xp << 16);
;             }
.LBB0_1429:
	s_mov_b32 s92, 1
	s_mov_b32 s93, 0
	s_mov_b32 s94, 0
	s_mov_b32 s95, 0x80000000
	v_mov_b32_e32 v120, 0
	v_mov_b32_e32 v121, 0
	v_mov_b32_e32 v122, 0
	v_mov_b32_e32 v123, 0
	v_mov_b32_e32 v124, 0
	v_mov_b32_e32 v125, 0
	v_mov_b32_e32 v126, 0
	v_mov_b32_e32 v127, 0
	v_mov_b32_e32 v128, 0
	v_mov_b32_e32 v129, 0
	v_mov_b32_e32 v130, 0
	v_mov_b32_e32 v131, 0
	v_mov_b32_e32 v132, 0
	v_mov_b32_e32 v133, 0
	v_mov_b32_e32 v134, 0
	v_mov_b32_e32 v135, 0
	v_mov_b32_e32 v136, 0
	v_mov_b32_e32 v137, 0
	s_and_b64 vcc, exec, s[2:3]
	s_cbranch_vccz .LBB0_1177
	s_ashr_i32 s53, s52, 31
	s_mul_i32 s3, s52, 0x8800
	v_readlane_b32 s4, v254, 23
	s_mul_hi_i32 s2, s52, 0x8800
	s_add_u32 s72, s4, s3
	v_readlane_b32 s3, v254, 25
	s_addc_u32 s73, s3, s2
	s_movk_i32 s2, 0x880
	v_cmp_gt_i32_e64 s[4:5], s2, v190
	s_movk_i32 s2, 0x680
	v_cmp_gt_i32_e64 s[6:7], s2, v190
	s_movk_i32 s2, 0x480
	v_cmp_gt_i32_e64 s[8:9], s2, v190
	s_movk_i32 s2, 0x280
	v_cmp_gt_i32_e64 s[10:11], s2, v190
	s_movk_i32 s2, 0x80
	v_cmp_gt_i32_e64 s[12:13], s2, v190
	s_lshl_b64 s[2:3], s[52:53], 2
	s_add_u32 s16, s2, 0x2000
	s_addc_u32 s17, s3, 0
	v_add_u32_e32 v73, 0x600, v190
	s_add_u32 s14, s87, s16
	v_cndmask_b32_e64 v62, 0, v190, s[4:5]
	v_cndmask_b32_e64 v64, 0, v191, s[6:7]
	v_cndmask_b32_e64 v66, 0, v192, s[8:9]
	v_cndmask_b32_e64 v68, 0, v73, s[10:11]
	v_add_u32_e32 v75, 0x800, v190
	s_addc_u32 s15, s88, s17
	v_ashrrev_i32_e32 v63, 31, v62
	v_ashrrev_i32_e32 v65, 31, v64
	v_ashrrev_i32_e32 v67, 31, v66
	v_ashrrev_i32_e32 v69, 31, v68
	v_cndmask_b32_e64 v70, 0, v75, s[12:13]
	s_add_u32 s62, s87, s2
	v_lshl_add_u64 v[0:1], v[62:63], 4, s[72:73]
	v_lshl_add_u64 v[4:5], v[64:65], 4, s[72:73]
	v_lshl_add_u64 v[8:9], v[66:67], 4, s[72:73]
	v_lshl_add_u64 v[12:13], v[68:69], 4, s[72:73]
	v_ashrrev_i32_e32 v71, 31, v70
	s_addc_u32 s63, s88, s3
	v_mov_b32_e32 v20, 0x5000
	v_mov_b32_e32 v31, 0
	global_load_dwordx4 v[0:3], v[0:1], off
	s_nop 0
	global_load_dwordx4 v[4:7], v[4:5], off
	s_nop 0
	global_load_dwordx4 v[8:11], v[8:9], off
	s_nop 0
	global_load_dwordx4 v[12:15], v[12:13], off
	v_lshl_add_u64 v[16:17], v[70:71], 4, s[72:73]
	global_load_dword v74, v20, s[62:63]
	v_mov_b32_e32 v20, 0x8000
	s_add_u32 s2, s89, s16
	global_load_dwordx4 v[16:19], v[16:17], off
	s_addc_u32 s3, s90, s17
	global_load_dword v72, v20, s[62:63]
	global_load_dword v76, v31, s[14:15]
	global_load_dword v78, v31, s[2:3]
	s_mul_i32 s3, s52, 0x4080
	s_mul_hi_i32 s2, s52, 0x4080
	s_add_u32 s48, s58, s3
	s_addc_u32 s49, s59, s2
	s_mov_b32 s2, 0xf07fc3e1
	v_mul_hi_i32 v20, v190, s2
	v_add_u32_e32 v20, v20, v190
	v_lshrrev_b32_e32 v21, 31, v20
	v_ashrrev_i32_e32 v20, 10, v20
	v_add_u32_e32 v97, v20, v21
	v_mul_i32_i24_e32 v20, 0x442, v97
	v_sub_u32_e32 v22, v190, v20
	s_movk_i32 s2, 0x1108
	v_cmp_gt_i32_e64 s[36:37], s2, v190
	v_subrev_u32_e32 v20, 28, v22
	s_movk_i32 s2, 0x402
	v_cmp_gt_u32_e64 s[46:47], s2, v20
	v_readfirstlane_b32 s51, v190
	s_and_b64 s[14:15], s[36:37], s[46:47]
	v_lshlrev_b32_e32 v32, 4, v22
	v_mov_b32_e32 v30, 0
	v_mov_b32_e32 v29, 0
	v_mov_b32_e32 v28, 0
	v_mov_b32_e32 v103, 0
	s_and_saveexec_b64 s[2:3], s[14:15]
	s_cbranch_execz .LBB0_1436
	v_mov_b64_e32 v[20:21], s[48:49]
	s_mov_b32 s14, 0x1020000
	v_mad_i64_i32 v[20:21], s[14:15], v97, s14, v[20:21]
	v_lshl_add_u64 v[20:21], v[20:21], 0, v[32:33]
	global_load_dwordx4 v[28:31], v[20:21], off offset:-352
	v_cmp_lt_u32_e32 vcc, 28, v22
	v_mov_b32_e32 v24, 0
	v_mov_b32_e32 v23, 0
	s_and_b64 vcc, vcc, s[92:93]
	s_and_saveexec_b64 s[14:15], vcc
	s_cbranch_execz .LBB0_1433
	global_load_ushort v120, v[20:21], off offset:-354
.LBB0_1433:
	s_or_b64 exec, exec, s[14:15]
	s_movk_i32 s14, 0x41d
	v_cmp_gt_u32_e32 vcc, s14, v22
	s_and_b64 vcc, vcc, s[94:95]
	s_and_saveexec_b64 s[14:15], vcc
	s_cbranch_execz .LBB0_1435
	global_load_ushort v121, v[20:21], off offset:-336

; template <int NQ, int NB, int L>
; __device__ __forceinline__ void conv_unit(LAS unsigned char* lds, const Args& a, int j, int seq0, int c, int tid) {
;     ...
;         for (int it = 0; it < NIT; ++it) {
;             const int idx = it * 512 + tid; const int b = idx / NCH, ch = idx % NCH, p = ch * 8 - PADL;
;             raws[it] = (u32x4){0u, 0u, 0u, 0u}; halos[it] = 0u;
;             if (idx < NB * NCH && p >= 0 && p < L) {
;                 const bf16_t* row = V + seq_off_ch(seq0 + b) + (size_t)c * LS + XPAD + p;
;                 raws[it] = *(const u32x4*)row;
;                 const unsigned xm = p > 0 ? (unsigned)row[-1] : 0u, xp = (p + 8 < L) ? (unsigned)row[8] : 0u;
;                 halos[it] = xm | (xp << 16);
;             }
.LBB0_1436:
	s_or_b64 exec, exec, s[2:3]
	s_mov_b32 s2, 0xf07fc3e1
	v_mul_hi_i32 v20, v191, s2
	v_add_u32_e32 v20, v20, v191
	v_lshrrev_b32_e32 v21, 31, v20
	v_ashrrev_i32_e32 v20, 10, v20
	v_add_u32_e32 v96, v20, v21
	v_mul_i32_i24_e32 v20, 0x442, v96
	v_sub_u32_e32 v22, v191, v20
	s_movk_i32 s2, 0xf08
	v_cmp_gt_i32_e64 s[30:31], s2, v190
	v_subrev_u32_e32 v20, 28, v22
	s_movk_i32 s2, 0x402
	v_cmp_gt_u32_e64 s[44:45], s2, v20
	s_and_b64 s[14:15], s[30:31], s[44:45]
	v_mov_b32_e32 v57, 0
	v_lshlrev_b32_e32 v94, 4, v22
	v_mov_b32_e32 v56, 0
	v_mov_b32_e32 v55, 0
	v_mov_b32_e32 v54, 0
	v_mov_b32_e32 v102, 0
	s_and_saveexec_b64 s[2:3], s[14:15]
	s_cbranch_execz .LBB0_1442
	v_mov_b64_e32 v[20:21], s[48:49]
	s_mov_b32 s14, 0x1020000
	v_mad_i64_i32 v[20:21], s[14:15], v96, s14, v[20:21]
	v_mov_b32_e32 v95, v33
	v_lshl_add_u64 v[20:21], v[20:21], 0, v[94:95]
	global_load_dwordx4 v[54:57], v[20:21], off offset:-352
	v_cmp_lt_u32_e32 vcc, 28, v22
	v_mov_b32_e32 v24, 0
	v_mov_b32_e32 v23, 0
	s_and_b64 vcc, vcc, s[92:93]
	s_and_saveexec_b64 s[14:15], vcc
	s_cbranch_execz .LBB0_1439
	global_load_ushort v122, v[20:21], off offset:-354
.LBB0_1439:
	s_or_b64 exec, exec, s[14:15]
	s_movk_i32 s14, 0x41d
	v_cmp_gt_u32_e32 vcc, s14, v22
	s_and_b64 vcc, vcc, s[94:95]
	s_and_saveexec_b64 s[14:15], vcc
	s_cbranch_execz .LBB0_1441
	global_load_ushort v123, v[20:21], off offset:-336

; template <int NQ, int NB, int L>
; __device__ __forceinline__ void conv_unit(LAS unsigned char* lds, const Args& a, int j, int seq0, int c, int tid) {
;     ...
;         for (int it = 0; it < NIT; ++it) {
;             const int idx = it * 512 + tid; const int b = idx / NCH, ch = idx % NCH, p = ch * 8 - PADL;
;             raws[it] = (u32x4){0u, 0u, 0u, 0u}; halos[it] = 0u;
;             if (idx < NB * NCH && p >= 0 && p < L) {
;                 const bf16_t* row = V + seq_off_ch(seq0 + b) + (size_t)c * LS + XPAD + p;
;                 raws[it] = *(const u32x4*)row;
;                 const unsigned xm = p > 0 ? (unsigned)row[-1] : 0u, xp = (p + 8 < L) ? (unsigned)row[8] : 0u;
;                 halos[it] = xm | (xp << 16);
;             }
.LBB0_1442:
	s_or_b64 exec, exec, s[2:3]
	s_mov_b32 s2, 0xf07fc3e1
	v_mul_hi_i32 v20, v192, s2
	v_add_u32_e32 v20, v20, v192
	v_lshrrev_b32_e32 v21, 31, v20
	v_ashrrev_i32_e32 v20, 10, v20
	v_add_u32_e32 v95, v20, v21
	v_mul_i32_i24_e32 v20, 0x442, v95
	v_sub_u32_e32 v22, v192, v20
	s_movk_i32 s2, 0xd08
	v_cmp_gt_i32_e64 s[26:27], s2, v190
	v_subrev_u32_e32 v20, 28, v22
	s_movk_i32 s2, 0x402
	v_cmp_gt_u32_e64 s[42:43], s2, v20
	s_and_b64 s[14:15], s[26:27], s[42:43]
	v_mov_b32_e32 v53, 0
	v_lshlrev_b32_e32 v92, 4, v22
	v_mov_b32_e32 v52, 0
	v_mov_b32_e32 v51, 0
	v_mov_b32_e32 v50, 0
	v_mov_b32_e32 v101, 0
	s_and_saveexec_b64 s[2:3], s[14:15]
	s_cbranch_execz .LBB0_1448
	v_mov_b64_e32 v[20:21], s[48:49]
	s_mov_b32 s14, 0x1020000
	v_mad_i64_i32 v[20:21], s[14:15], v95, s14, v[20:21]
	v_mov_b32_e32 v93, v33
	v_lshl_add_u64 v[20:21], v[20:21], 0, v[92:93]
	global_load_dwordx4 v[50:53], v[20:21], off offset:-352
	v_cmp_lt_u32_e32 vcc, 28, v22
	v_mov_b32_e32 v24, 0
	v_mov_b32_e32 v23, 0
	s_and_b64 vcc, vcc, s[92:93]
	s_and_saveexec_b64 s[14:15], vcc
	s_cbranch_execz .LBB0_1445
	global_load_ushort v124, v[20:21], off offset:-354
.LBB0_1445:
	s_or_b64 exec, exec, s[14:15]
	s_movk_i32 s14, 0x41d
	v_cmp_gt_u32_e32 vcc, s14, v22
	s_and_b64 vcc, vcc, s[94:95]
	s_and_saveexec_b64 s[14:15], vcc
	s_cbranch_execz .LBB0_1447
	global_load_ushort v125, v[20:21], off offset:-336

; template <int NQ, int NB, int L>
; __device__ __forceinline__ void conv_unit(LAS unsigned char* lds, const Args& a, int j, int seq0, int c, int tid) {
;     ...
;         for (int it = 0; it < NIT; ++it) {
;             const int idx = it * 512 + tid; const int b = idx / NCH, ch = idx % NCH, p = ch * 8 - PADL;
;             raws[it] = (u32x4){0u, 0u, 0u, 0u}; halos[it] = 0u;
;             if (idx < NB * NCH && p >= 0 && p < L) {
;                 const bf16_t* row = V + seq_off_ch(seq0 + b) + (size_t)c * LS + XPAD + p;
;                 raws[it] = *(const u32x4*)row;
;                 const unsigned xm = p > 0 ? (unsigned)row[-1] : 0u, xp = (p + 8 < L) ? (unsigned)row[8] : 0u;
;                 halos[it] = xm | (xp << 16);
;             }
.LBB0_1448:
	s_or_b64 exec, exec, s[2:3]
	s_mov_b32 s2, 0xf07fc3e1
	v_mul_hi_i32 v20, v73, s2
	v_add_u32_e32 v20, v20, v73
	v_lshrrev_b32_e32 v21, 31, v20
	v_ashrrev_i32_e32 v20, 10, v20
	v_add_u32_e32 v93, v20, v21
	v_mul_i32_i24_e32 v20, 0x442, v93
	v_sub_u32_e32 v22, v73, v20
	s_movk_i32 s2, 0xb08
	v_cmp_gt_i32_e64 s[22:23], s2, v190
	v_subrev_u32_e32 v20, 28, v22
	s_movk_i32 s2, 0x402
	v_cmp_gt_u32_e64 s[40:41], s2, v20
	s_and_b64 s[14:15], s[22:23], s[40:41]
	v_mov_b32_e32 v49, 0
	v_lshlrev_b32_e32 v90, 4, v22
	v_mov_b32_e32 v48, 0
	v_mov_b32_e32 v47, 0
	v_mov_b32_e32 v46, 0
	v_mov_b32_e32 v100, 0
	s_and_saveexec_b64 s[2:3], s[14:15]
	s_cbranch_execz .LBB0_1454
	v_mov_b64_e32 v[20:21], s[48:49]
	s_mov_b32 s14, 0x1020000
	v_mad_i64_i32 v[20:21], s[14:15], v93, s14, v[20:21]
	v_mov_b32_e32 v91, v33
	v_lshl_add_u64 v[20:21], v[20:21], 0, v[90:91]
	global_load_dwordx4 v[46:49], v[20:21], off offset:-352
	v_cmp_lt_u32_e32 vcc, 28, v22
	v_mov_b32_e32 v24, 0
	v_mov_b32_e32 v23, 0
	s_and_b64 vcc, vcc, s[92:93]
	s_and_saveexec_b64 s[14:15], vcc
	s_cbranch_execz .LBB0_1451
	global_load_ushort v126, v[20:21], off offset:-354
.LBB0_1451:
	s_or_b64 exec, exec, s[14:15]
	s_movk_i32 s14, 0x41d
	v_cmp_gt_u32_e32 vcc, s14, v22
	s_and_b64 vcc, vcc, s[94:95]
	s_and_saveexec_b64 s[14:15], vcc
	s_cbranch_execz .LBB0_1453
	global_load_ushort v127, v[20:21], off offset:-336

; template <int NQ, int NB, int L>
; __device__ __forceinline__ void conv_unit(LAS unsigned char* lds, const Args& a, int j, int seq0, int c, int tid) {
;     ...
;         for (int it = 0; it < NIT; ++it) {
;             const int idx = it * 512 + tid; const int b = idx / NCH, ch = idx % NCH, p = ch * 8 - PADL;
;             raws[it] = (u32x4){0u, 0u, 0u, 0u}; halos[it] = 0u;
;             if (idx < NB * NCH && p >= 0 && p < L) {
;                 const bf16_t* row = V + seq_off_ch(seq0 + b) + (size_t)c * LS + XPAD + p;
;                 raws[it] = *(const u32x4*)row;
;                 const unsigned xm = p > 0 ? (unsigned)row[-1] : 0u, xp = (p + 8 < L) ? (unsigned)row[8] : 0u;
;                 halos[it] = xm | (xp << 16);
;             }
.LBB0_1454:
	s_or_b64 exec, exec, s[2:3]
	s_mov_b32 s2, 0xf07fc3e1
	v_mul_hi_i32 v20, v75, s2
	v_add_u32_e32 v20, v20, v75
	v_lshrrev_b32_e32 v21, 31, v20
	v_ashrrev_i32_e32 v20, 10, v20
	v_add_u32_e32 v91, v20, v21
	v_mul_i32_i24_e32 v20, 0x442, v91
	v_sub_u32_e32 v22, v75, v20
	s_movk_i32 s2, 0x908
	v_cmp_gt_i32_e64 s[18:19], s2, v190
	v_subrev_u32_e32 v20, 28, v22
	s_movk_i32 s2, 0x402
	v_cmp_gt_u32_e64 s[38:39], s2, v20
	s_and_b64 s[14:15], s[18:19], s[38:39]
	v_mov_b32_e32 v45, 0
	v_lshlrev_b32_e32 v88, 4, v22
	v_mov_b32_e32 v44, 0
	v_mov_b32_e32 v43, 0
	v_mov_b32_e32 v42, 0
	v_mov_b32_e32 v99, 0
	s_and_saveexec_b64 s[2:3], s[14:15]
	s_cbranch_execz .LBB0_1460
	v_mov_b64_e32 v[20:21], s[48:49]
	s_mov_b32 s14, 0x1020000
	v_mad_i64_i32 v[20:21], s[14:15], v91, s14, v[20:21]
	v_mov_b32_e32 v89, v33
	v_lshl_add_u64 v[20:21], v[20:21], 0, v[88:89]
	global_load_dwordx4 v[42:45], v[20:21], off offset:-352
	v_cmp_lt_u32_e32 vcc, 28, v22
	v_mov_b32_e32 v24, 0
	v_mov_b32_e32 v23, 0
	s_and_b64 vcc, vcc, s[92:93]
	s_and_saveexec_b64 s[14:15], vcc
	s_cbranch_execz .LBB0_1457
	global_load_ushort v128, v[20:21], off offset:-354
.LBB0_1457:
	s_or_b64 exec, exec, s[14:15]
	s_movk_i32 s14, 0x41d
	v_cmp_gt_u32_e32 vcc, s14, v22
	s_and_b64 vcc, vcc, s[94:95]
	s_and_saveexec_b64 s[14:15], vcc
	s_cbranch_execz .LBB0_1459
	global_load_ushort v129, v[20:21], off offset:-336

; template <int NQ, int NB, int L>
; __device__ __forceinline__ void conv_unit(LAS unsigned char* lds, const Args& a, int j, int seq0, int c, int tid) {
;     ...
;         for (int it = 0; it < NIT; ++it) {
;             const int idx = it * 512 + tid; const int b = idx / NCH, ch = idx % NCH, p = ch * 8 - PADL;
;             raws[it] = (u32x4){0u, 0u, 0u, 0u}; halos[it] = 0u;
;             if (idx < NB * NCH && p >= 0 && p < L) {
;                 const bf16_t* row = V + seq_off_ch(seq0 + b) + (size_t)c * LS + XPAD + p;
;                 raws[it] = *(const u32x4*)row;
;                 const unsigned xm = p > 0 ? (unsigned)row[-1] : 0u, xp = (p + 8 < L) ? (unsigned)row[8] : 0u;
;                 halos[it] = xm | (xp << 16);
;             }
.LBB0_1460:
	s_or_b64 exec, exec, s[2:3]
	v_add_u32_e32 v20, 0xa00, v190
	s_mov_b32 s2, 0xf07fc3e1
	v_mul_hi_i32 v21, v20, s2
	v_add_u32_e32 v21, v21, v20
	v_lshrrev_b32_e32 v22, 31, v21
	v_ashrrev_i32_e32 v21, 10, v21
	v_add_u32_e32 v89, v21, v22
	v_mul_i32_i24_e32 v21, 0x442, v89
	v_sub_u32_e32 v22, v20, v21
	s_movk_i32 s2, 0x708
	v_cmp_gt_i32_e64 s[16:17], s2, v190
	v_subrev_u32_e32 v20, 28, v22
	s_movk_i32 s2, 0x402
	v_cmp_gt_u32_e64 s[34:35], s2, v20
	s_and_b64 s[14:15], s[16:17], s[34:35]
	v_mov_b32_e32 v41, 0
	v_lshlrev_b32_e32 v86, 4, v22
	v_mov_b32_e32 v40, 0
	v_mov_b32_e32 v39, 0
	v_mov_b32_e32 v38, 0
	v_mov_b32_e32 v98, 0
	s_and_saveexec_b64 s[2:3], s[14:15]
	s_cbranch_execz .LBB0_1466
	v_mov_b64_e32 v[20:21], s[48:49]
	s_mov_b32 s14, 0x1020000
	v_mad_i64_i32 v[20:21], s[14:15], v89, s14, v[20:21]
	v_mov_b32_e32 v87, v33
	v_lshl_add_u64 v[20:21], v[20:21], 0, v[86:87]
	global_load_dwordx4 v[38:41], v[20:21], off offset:-352
	v_cmp_lt_u32_e32 vcc, 28, v22
	v_mov_b32_e32 v24, 0
	v_mov_b32_e32 v23, 0
	s_and_b64 vcc, vcc, s[92:93]
	s_and_saveexec_b64 s[14:15], vcc
	s_cbranch_execz .LBB0_1463
	global_load_ushort v130, v[20:21], off offset:-354
.LBB0_1463:
	s_or_b64 exec, exec, s[14:15]
	s_movk_i32 s14, 0x41d
	v_cmp_gt_u32_e32 vcc, s14, v22
	s_and_b64 vcc, vcc, s[94:95]
	s_and_saveexec_b64 s[14:15], vcc
	s_cbranch_execz .LBB0_1465
	global_load_ushort v131, v[20:21], off offset:-336

; template <int NQ, int NB, int L>
; __device__ __forceinline__ void conv_unit(LAS unsigned char* lds, const Args& a, int j, int seq0, int c, int tid) {
;     ...
;         for (int it = 0; it < NIT; ++it) {
;             const int idx = it * 512 + tid; const int b = idx / NCH, ch = idx % NCH, p = ch * 8 - PADL;
;             raws[it] = (u32x4){0u, 0u, 0u, 0u}; halos[it] = 0u;
;             if (idx < NB * NCH && p >= 0 && p < L) {
;                 const bf16_t* row = V + seq_off_ch(seq0 + b) + (size_t)c * LS + XPAD + p;
;                 raws[it] = *(const u32x4*)row;
;                 const unsigned xm = p > 0 ? (unsigned)row[-1] : 0u, xp = (p + 8 < L) ? (unsigned)row[8] : 0u;
;                 halos[it] = xm | (xp << 16);
;             }
.LBB0_1466:
	s_or_b64 exec, exec, s[2:3]
	v_add_u32_e32 v20, 0xc00, v190
	s_mov_b32 s2, 0xf07fc3e1
	v_mul_hi_i32 v21, v20, s2
	v_add_u32_e32 v21, v21, v20
	v_lshrrev_b32_e32 v22, 31, v21
	v_ashrrev_i32_e32 v21, 10, v21
	v_add_u32_e32 v87, v21, v22
	v_mul_i32_i24_e32 v21, 0x442, v87
	v_sub_u32_e32 v22, v20, v21
	s_movk_i32 s2, 0x508
	v_cmp_gt_i32_e64 s[14:15], s2, v190
	v_subrev_u32_e32 v20, 28, v22
	s_movk_i32 s2, 0x402
	v_cmp_gt_u32_e64 s[28:29], s2, v20
	s_and_b64 s[20:21], s[14:15], s[28:29]
	v_mov_b32_e32 v37, 0
	v_lshlrev_b32_e32 v84, 4, v22
	v_mov_b32_e32 v36, 0
	v_mov_b32_e32 v35, 0
	v_mov_b32_e32 v34, 0
	v_mov_b32_e32 v85, 0
	s_and_saveexec_b64 s[2:3], s[20:21]
	s_cbranch_execz .LBB0_1472
	v_mov_b64_e32 v[20:21], s[48:49]
	s_mov_b32 s20, 0x1020000
	v_mad_i64_i32 v[20:21], s[20:21], v87, s20, v[20:21]
	v_mov_b32_e32 v85, v33
	v_lshl_add_u64 v[20:21], v[20:21], 0, v[84:85]
	global_load_dwordx4 v[34:37], v[20:21], off offset:-352
	v_cmp_lt_u32_e32 vcc, 28, v22
	v_mov_b32_e32 v24, 0
	v_mov_b32_e32 v23, 0
	s_and_b64 vcc, vcc, s[92:93]
	s_and_saveexec_b64 s[20:21], vcc
	s_cbranch_execz .LBB0_1469
	global_load_ushort v132, v[20:21], off offset:-354
.LBB0_1469:
	s_or_b64 exec, exec, s[20:21]
	s_movk_i32 s20, 0x41d
	v_cmp_gt_u32_e32 vcc, s20, v22
	s_and_b64 vcc, vcc, s[94:95]
	s_and_saveexec_b64 s[20:21], vcc
	s_cbranch_execz .LBB0_1471
	global_load_ushort v133, v[20:21], off offset:-336

; template <int NQ, int NB, int L>
; __device__ __forceinline__ void conv_unit(LAS unsigned char* lds, const Args& a, int j, int seq0, int c, int tid) {
;     ...
;         for (int it = 0; it < NIT; ++it) {
;             const int idx = it * 512 + tid; const int b = idx / NCH, ch = idx % NCH, p = ch * 8 - PADL;
;             raws[it] = (u32x4){0u, 0u, 0u, 0u}; halos[it] = 0u;
;             if (idx < NB * NCH && p >= 0 && p < L) {
;                 const bf16_t* row = V + seq_off_ch(seq0 + b) + (size_t)c * LS + XPAD + p;
;                 raws[it] = *(const u32x4*)row;
;                 const unsigned xm = p > 0 ? (unsigned)row[-1] : 0u, xp = (p + 8 < L) ? (unsigned)row[8] : 0u;
;                 halos[it] = xm | (xp << 16);
;             }
.LBB0_1472:
	s_or_b64 exec, exec, s[2:3]
	v_add_u32_e32 v20, 0xe00, v190
	s_mov_b32 s2, 0xf07fc3e1
	v_mul_hi_i32 v21, v20, s2
	v_add_u32_e32 v21, v21, v20
	v_lshrrev_b32_e32 v22, 31, v21
	v_ashrrev_i32_e32 v21, 10, v21
	v_add_u32_e32 v79, v21, v22
	v_mul_i32_i24_e32 v21, 0x442, v79
	v_sub_u32_e32 v22, v20, v21
	s_movk_i32 s2, 0x308
	v_subrev_u32_e32 v20, 28, v22
	s_movk_i32 s20, 0x402
	v_cmp_gt_i32_e64 s[2:3], s2, v190
	v_cmp_gt_u32_e64 s[24:25], s20, v20
	s_and_b64 s[66:67], s[2:3], s[24:25]
	v_mov_b32_e32 v27, 0
	v_lshlrev_b32_e32 v82, 4, v22
	v_mov_b32_e32 v26, 0
	v_mov_b32_e32 v25, 0
	v_mov_b32_e32 v24, 0
	v_mov_b32_e32 v83, 0
	s_and_saveexec_b64 s[20:21], s[66:67]
	s_cbranch_execz .LBB0_1478
	v_mov_b64_e32 v[20:21], s[48:49]
	s_mov_b32 s50, 0x1020000
	v_mad_i64_i32 v[20:21], s[66:67], v79, s50, v[20:21]
	v_mov_b32_e32 v83, v33
	v_lshl_add_u64 v[20:21], v[20:21], 0, v[82:83]
	global_load_dwordx4 v[24:27], v[20:21], off offset:-352
	v_cmp_lt_u32_e32 vcc, 28, v22
	v_mov_b32_e32 v58, 0
	v_mov_b32_e32 v23, 0
	s_and_b64 vcc, vcc, s[92:93]
	s_and_saveexec_b64 s[66:67], vcc
	s_cbranch_execz .LBB0_1475
	global_load_ushort v134, v[20:21], off offset:-354
.LBB0_1475:
	s_or_b64 exec, exec, s[66:67]
	s_movk_i32 s50, 0x41d
	v_cmp_gt_u32_e32 vcc, s50, v22
	s_and_b64 vcc, vcc, s[94:95]
	s_and_saveexec_b64 s[66:67], vcc
	s_cbranch_execz .LBB0_1477
	global_load_ushort v135, v[20:21], off offset:-336

; template <int NQ, int NB, int L>
; __device__ __forceinline__ void conv_unit(LAS unsigned char* lds, const Args& a, int j, int seq0, int c, int tid) {
;     ...
;         for (int it = 0; it < NIT; ++it) {
;             const int idx = it * 512 + tid; const int b = idx / NCH, ch = idx % NCH, p = ch * 8 - PADL;
;             raws[it] = (u32x4){0u, 0u, 0u, 0u}; halos[it] = 0u;
;             if (idx < NB * NCH && p >= 0 && p < L) {
;                 const bf16_t* row = V + seq_off_ch(seq0 + b) + (size_t)c * LS + XPAD + p;
;                 raws[it] = *(const u32x4*)row;
;                 const unsigned xm = p > 0 ? (unsigned)row[-1] : 0u, xp = (p + 8 < L) ? (unsigned)row[8] : 0u;
;                 halos[it] = xm | (xp << 16);
;             }
.LBB0_1478:
	s_or_b64 exec, exec, s[20:21]
	v_add_u32_e32 v20, 0x1000, v190
	s_mov_b32 s20, 0xf07fc3e1
	v_mul_hi_i32 v21, v20, s20
	v_add_u32_e32 v21, v21, v20
	v_lshrrev_b32_e32 v22, 31, v21
	v_ashrrev_i32_e32 v21, 10, v21
	v_add_u32_e32 v77, v21, v22
	v_mul_i32_i24_e32 v21, 0x442, v77
	v_sub_u32_e32 v60, v20, v21
	s_movk_i32 s20, 0x108
	v_cmp_gt_i32_e32 vcc, s20, v190
	v_subrev_u32_e32 v20, 28, v60
	s_movk_i32 s20, 0x402
	v_cmp_gt_u32_e64 s[20:21], s20, v20
	s_and_b64 s[70:71], vcc, s[20:21]
	v_mov_b32_e32 v23, 0
	v_lshlrev_b32_e32 v80, 4, v60
	v_mov_b32_e32 v22, 0
	v_mov_b32_e32 v21, 0
	v_mov_b32_e32 v20, 0
	v_mov_b32_e32 v81, 0
	s_and_saveexec_b64 s[66:67], s[70:71]
	s_cbranch_execz .LBB0_1484
	v_mov_b64_e32 v[20:21], s[48:49]
	s_mov_b32 s48, 0x1020000
	v_mad_i64_i32 v[20:21], s[48:49], v77, s48, v[20:21]
	v_mov_b32_e32 v81, v33
	v_lshl_add_u64 v[58:59], v[20:21], 0, v[80:81]
	global_load_dwordx4 v[20:23], v[58:59], off offset:-352
	v_cmp_lt_u32_e64 s[48:49], 28, v60
	v_mov_b32_e32 v81, 0
	v_mov_b32_e32 v61, 0
	s_and_b64 s[48:49], s[48:49], s[92:93]
	s_and_saveexec_b64 s[70:71], s[48:49]
	s_cbranch_execz .LBB0_1481
	global_load_ushort v136, v[58:59], off offset:-354
.LBB0_1481:
	s_or_b64 exec, exec, s[70:71]
	s_movk_i32 s48, 0x41d
	v_cmp_gt_u32_e64 s[48:49], s48, v60
	s_and_b64 s[48:49], s[48:49], s[94:95]
	s_and_saveexec_b64 s[70:71], s[48:49]
	s_cbranch_execz .LBB0_1483
	global_load_ushort v137, v[58:59], off offset:-336

; __device__ __forceinline__ unsigned cvtpk(float lo, float hi) { f32x2 v = {lo, hi}; bf16x2_t b = __builtin_convertvector(v, bf16x2_t); return __builtin_bit_cast(unsigned, b); }
; template <int NQ, int NB, int L>
; __device__ __forceinline__ void conv_unit(LAS unsigned char* lds, const Args& a, int j, int seq0, int c, int tid) {
;     ...
;                 const unsigned xm = p > 0 ? (unsigned)row[-1] : 0u, xp = (p + 8 < L) ? (unsigned)row[8] : 0u;
;                 halos[it] = xm | (xp << 16);
;             }
;         }
; #pragma unroll
;         for (int it = 0; it < NIT; ++it) {
;             const int idx = it * 512 + tid; const int b = idx / NCH, ch = idx % NCH, p = ch * 8 - PADL;
;             u32x4 o = {0u, 0u, 0u, 0u};
;             if (p >= 0 && p < L) {
;                 const u32x4 raw = raws[it];
;                 float x[10];
;                 x[0] = bflo(halos[it]); x[9] = bfhi(halos[it]);
;                 x[1] = bflo(raw.x); x[2] = bfhi(raw.x); x[3] = bflo(raw.y); x[4] = bfhi(raw.y); x[5] = bflo(raw.z); x[6] = bfhi(raw.z); x[7] = bflo(raw.w); x[8] = bfhi(raw.w);
;                 float y[8];
; #pragma unroll
;                 for (int i = 0; i < 8; ++i) y[i] = w0 * x[i] + w1 * x[i + 1] + w2 * x[i + 2] + bb;
;                 o.x = cvtpk(y[0], y[1]); o.y = cvtpk(y[2], y[3]); o.z = cvtpk(y[4], y[5]); o.w = cvtpk(y[6], y[7]);
.LBB0_1484:
	s_or_b64 exec, exec, s[66:67]
	s_waitcnt vmcnt(0)
	v_mov_b32_dpp v140, v31 wave_shr:1 row_mask:0xf bank_mask:0xf bound_ctrl:0
	v_mov_b32_dpp v141, v28 wave_shl:1 row_mask:0xf bank_mask:0xf bound_ctrl:0
	v_lshrrev_b32_e32 v140, 16, v140
	v_and_b32_e32 v141, 0xffff, v141
	v_or_b32_e32 v120, v120, v140
	v_or_b32_e32 v121, v121, v141
	v_lshl_or_b32 v103, v121, 16, v120
	v_mov_b32_dpp v140, v57 wave_shr:1 row_mask:0xf bank_mask:0xf bound_ctrl:0
	v_mov_b32_dpp v141, v54 wave_shl:1 row_mask:0xf bank_mask:0xf bound_ctrl:0
	v_lshrrev_b32_e32 v140, 16, v140
	v_and_b32_e32 v141, 0xffff, v141
	v_or_b32_e32 v122, v122, v140
	v_or_b32_e32 v123, v123, v141
	v_lshl_or_b32 v102, v123, 16, v122
	v_mov_b32_dpp v140, v53 wave_shr:1 row_mask:0xf bank_mask:0xf bound_ctrl:0
	v_mov_b32_dpp v141, v50 wave_shl:1 row_mask:0xf bank_mask:0xf bound_ctrl:0
	v_lshrrev_b32_e32 v140, 16, v140
	v_and_b32_e32 v141, 0xffff, v141
	v_or_b32_e32 v124, v124, v140
	v_or_b32_e32 v125, v125, v141
	v_lshl_or_b32 v101, v125, 16, v124
	v_mov_b32_dpp v140, v49 wave_shr:1 row_mask:0xf bank_mask:0xf bound_ctrl:0
	v_mov_b32_dpp v141, v46 wave_shl:1 row_mask:0xf bank_mask:0xf bound_ctrl:0
	v_lshrrev_b32_e32 v140, 16, v140
	v_and_b32_e32 v141, 0xffff, v141
	v_or_b32_e32 v126, v126, v140
	v_or_b32_e32 v127, v127, v141
	v_lshl_or_b32 v100, v127, 16, v126
	v_mov_b32_dpp v140, v45 wave_shr:1 row_mask:0xf bank_mask:0xf bound_ctrl:0
	v_mov_b32_dpp v141, v42 wave_shl:1 row_mask:0xf bank_mask:0xf bound_ctrl:0
	v_lshrrev_b32_e32 v140, 16, v140
	v_and_b32_e32 v141, 0xffff, v141
	v_or_b32_e32 v128, v128, v140
	v_or_b32_e32 v129, v129, v141
	v_lshl_or_b32 v99, v129, 16, v128
	v_mov_b32_dpp v140, v41 wave_shr:1 row_mask:0xf bank_mask:0xf bound_ctrl:0
	v_mov_b32_dpp v141, v38 wave_shl:1 row_mask:0xf bank_mask:0xf bound_ctrl:0
	v_lshrrev_b32_e32 v140, 16, v140
	v_and_b32_e32 v141, 0xffff, v141
	v_or_b32_e32 v130, v130, v140
	v_or_b32_e32 v131, v131, v141
	v_lshl_or_b32 v98, v131, 16, v130
	v_mov_b32_dpp v140, v37 wave_shr:1 row_mask:0xf bank_mask:0xf bound_ctrl:0
	v_mov_b32_dpp v141, v34 wave_shl:1 row_mask:0xf bank_mask:0xf bound_ctrl:0
	v_lshrrev_b32_e32 v140, 16, v140
	v_and_b32_e32 v141, 0xffff, v141
	v_or_b32_e32 v132, v132, v140
	v_or_b32_e32 v133, v133, v141
	v_lshl_or_b32 v85, v133, 16, v132
	v_mov_b32_dpp v140, v27 wave_shr:1 row_mask:0xf bank_mask:0xf bound_ctrl:0
	v_mov_b32_dpp v141, v24 wave_shl:1 row_mask:0xf bank_mask:0xf bound_ctrl:0
	v_lshrrev_b32_e32 v140, 16, v140
	v_and_b32_e32 v141, 0xffff, v141
	v_or_b32_e32 v134, v134, v140
	v_or_b32_e32 v135, v135, v141
	v_lshl_or_b32 v83, v135, 16, v134
	v_mov_b32_dpp v140, v23 wave_shr:1 row_mask:0xf bank_mask:0xf bound_ctrl:0
	v_mov_b32_dpp v141, v20 wave_shl:1 row_mask:0xf bank_mask:0xf bound_ctrl:0
	v_lshrrev_b32_e32 v140, 16, v140
	v_and_b32_e32 v141, 0xffff, v141
	v_or_b32_e32 v136, v136, v140
	v_or_b32_e32 v137, v137, v141
	v_lshl_or_b32 v81, v137, 16, v136
	v_mov_b32_e32 v58, 0
	v_mov_b32_e32 v59, 0
	v_mov_b32_e32 v60, 0
	v_mov_b32_e32 v61, 0
	s_and_saveexec_b64 s[48:49], s[46:47]
	s_cbranch_execz .LBB0_1486
	v_and_b32_e32 v110, 0xffff0000, v28
	v_and_b32_e32 v109, 16, v30
	v_and_b32_e32 v108, 0xffff0000, v29
	v_lshlrev_b32_e32 v113, 16, v29
	v_mov_b32_e32 v112, v110
	v_and_b32_e32 v59, 16, v31
	v_and_b32_e32 v58, 0xffff0000, v30
	v_lshlrev_b32_e32 v61, 16, v31
	v_and_b32_e32 v104, 0xffff0000, v31
	v_lshlrev_b32_e32 v31, 16, v30
	v_mov_b32_e32 v30, v108
	v_pk_mov_b32 v[108:109], v[112:113], v[108:109] op_sel:[1,0]
	v_mov_b32_e32 v60, v58
	v_and_b32_e32 v105, 0xffff0000, v103
	v_and_b32_e32 v111, 16, v29
	v_lshlrev_b32_e32 v29, 16, v28
	v_lshlrev_b32_e32 v28, 16, v103
	s_waitcnt vmcnt(4)
	v_pk_mul_f32 v[108:109], v[74:75], v[108:109] op_sel_hi:[0,1]
	v_pk_mov_b32 v[58:59], v[30:31], v[58:59] op_sel:[1,0]
	v_pk_mov_b32 v[106:107], v[60:61], v[104:105] op_sel:[1,0]
	v_pk_mov_b32 v[110:111], v[28:29], v[110:111] op_sel:[1,0]
	s_waitcnt vmcnt(1)
	v_pk_fma_f32 v[108:109], v[76:77], v[112:113], v[108:109] op_sel_hi:[0,1,1]
	v_pk_mul_f32 v[58:59], v[74:75], v[58:59] op_sel_hi:[0,1]
	v_pk_mul_f32 v[110:111], v[74:75], v[110:111] op_sel_hi:[0,1]
	v_pk_fma_f32 v[108:109], v[72:73], v[30:31], v[108:109] op_sel_hi:[0,1,1]
	v_pk_fma_f32 v[30:31], v[76:77], v[30:31], v[58:59] op_sel_hi:[0,1,1]
	v_pk_mul_f32 v[58:59], v[74:75], v[106:107] op_sel_hi:[0,1]
	v_pk_fma_f32 v[28:29], v[76:77], v[28:29], v[110:111] op_sel_hi:[0,1,1]
	v_pk_fma_f32 v[58:59], v[76:77], v[60:61], v[58:59] op_sel_hi:[0,1,1]
	v_pk_fma_f32 v[28:29], v[72:73], v[112:113], v[28:29] op_sel_hi:[0,1,1]
	v_pk_fma_f32 v[30:31], v[72:73], v[60:61], v[30:31] op_sel_hi:[0,1,1]
	v_pk_fma_f32 v[58:59], v[72:73], v[104:105], v[58:59] op_sel_hi:[0,1,1]
	s_waitcnt vmcnt(0)
	v_pk_add_f32 v[28:29], v[78:79], v[28:29] op_sel_hi:[0,1]
	v_pk_add_f32 v[108:109], v[78:79], v[108:109] op_sel_hi:[0,1]
	v_pk_add_f32 v[30:31], v[78:79], v[30:31] op_sel_hi:[0,1]
	v_pk_add_f32 v[104:105], v[78:79], v[58:59] op_sel_hi:[0,1]
	v_cvt_pk_bf16_f32 v58, v28, v29
	v_cvt_pk_bf16_f32 v59, v108, v109
	v_cvt_pk_bf16_f32 v60, v30, v31
	v_cvt_pk_bf16_f32 v61, v104, v105
